# plus: first two vmcnt waits of the peeled first K-iteration relaxed after an epilogue (do not wait for the epilogue stores; pieces needed were issued before them)
# speedup vs baseline: 1.0011x; 1.0011x over previous
; __device__ __forceinline__ int tid_of(int wave_id) { int t = wave_id * 64 + lane_id(); asm volatile("" : "+v"(t)); return t; }
; #define PG8_STAGE(bufoff, gbase, voff) do { _Pragma("unroll") for (int _i = 0; _i < 2; ++_i) \
;         __builtin_amdgcn_global_load_lds((const unsigned*)((const char*)(gbase) + (voff)[_i]), (PG8_LAS unsigned*)(lds + (bufoff) + ldsw + _i * 8192), 16, 0, 0); } while (0)
; #define PG8_WAIT_V(n) asm volatile("s_waitcnt vmcnt(" #n ")" ::: "memory")
; #define PG8_BAR __builtin_amdgcn_s_barrier()
; template <class Epi, class Sched, bool ALIGN_EPI = false, bool SP2 = false>
; __device__ __forceinline__ void gemm_phase(PG8_LAS unsigned char* lds, const Gemm g, const Sched& S, const Epi& E, const int wave_id_in) {
;     int tid_o = tid_of(wave_id_in);
;     const int tid = tid_o, wid = __builtin_amdgcn_readfirstlane(tid >> 6), lane = tid & 63, wr = wid >> 2, wc = wid & 3, fr = lane & 15, fq = lane >> 4;
;     const int K = g.K, nt = K / BK;
;     unsigned voffA[2], voffB[2];
; #pragma unroll
;     for (int i = 0; i < 2; ++i) { int R, C; stage_rc(tid * 16 + i * 8192, R, C); const int Rb = Epi::PERM ? ((R & ~31) + perm32(R & 31)) : R;
;         voffA[i] = (unsigned)(R * K + C) * 2u; voffB[i] = (unsigned)(Rb * K + C) * 2u; }
;     const size_t kstep = (size_t)(BK * 2);
;     const size_t hstep = (size_t)HALF * K * 2;
;     const size_t tstep = 2 * hstep;
;     const unsigned ldsw = (unsigned)wid * 1024u;
;     const int aoff = lds_byte(wr * 64 + fr, fq * 8), boff = lds_byte(wc * 32 + fr, fq * 8);
;     ...
;         PG8_STAGE(PG8_SB(0, 0), cB, voffB); PG8_STAGE(PG8_SB(0, 1), cB + hstep, voffB); PG8_STAGE(PG8_SA(0, 0), cA, voffA); PG8_STAGE(PG8_SA(0, 1), cA + hstep, voffA);
;         if (wr == 1) PG8_BAR;
;         PG8_WAIT_V(2); PG8_BAR;
;         PG8_STAGE(PG8_SB(1, 0), cB + kstep, voffB); PG8_STAGE(PG8_SA(1, 0), cA + kstep, voffA); PG8_STAGE(PG8_SB(1, 1), cB + hstep + kstep, voffB);
;         PG8_WAIT_V(6); PG8_BAR;
.LBB0_123:
	s_mov_b64 s[30:31], 0x80
	s_and_b32 s24, s21, 3
	s_add_i32 m0, s65, 0x18000
	v_lshl_add_u64 v[6:7], v[6:7], 0, s[30:31]
	s_lshl_b32 s84, s79, 6
	s_lshl_b32 s25, s79, 13
	s_lshl_b32 s85, s24, 5
	s_lshl_b32 s26, s24, 12
	s_waitcnt vmcnt(2)
	s_barrier
	global_load_lds_dwordx4 v[6:7], off
	v_lshl_add_u64 v[4:5], v[4:5], 0, s[30:31]
	s_add_i32 m0, s65, 0x1a000
	s_add_i32 s86, s65, 0x8000
	s_add_i32 s87, s65, 0xa000
	global_load_lds_dwordx4 v[4:5], off
	v_lshl_add_u64 v[0:1], v[0:1], 0, s[30:31]
	s_mov_b32 m0, s86
	s_add_u32 s4, s68, 0x80080
	global_load_lds_dwordx4 v[0:1], off
	v_lshl_add_u64 v[0:1], v[2:3], 0, s[30:31]
	s_mov_b32 m0, s87
	s_addc_u32 s5, s69, 0
	global_load_lds_dwordx4 v[0:1], off
	s_add_i32 m0, s65, 0x1c000
	v_lshl_add_u64 v[0:1], s[4:5], 0, v[200:201]
	global_load_lds_dwordx4 v[0:1], off
	v_lshl_add_u64 v[0:1], s[4:5], 0, v[202:203]
	s_add_i32 m0, s65, 0x1e000
	s_movk_i32 s4, 0x3c0
	global_load_lds_dwordx4 v[0:1], off
	v_and_b32_e32 v0, 48, v8
	v_lshlrev_b32_e32 v1, 6, v8
	s_cmpk_lt_u32 s20, 0x100
	v_and_or_b32 v0, v1, s4, v0
	s_cselect_b64 s[34:35], -1, 0
	s_lshl_b32 s4, s21, 4
	s_and_b32 s88, s4, 16
	s_and_b32 s20, s85, 64
	s_cmp_lt_u32 s24, 2
	v_lshlrev_b32_e32 v1, 2, v8
	s_cselect_b64 s[4:5], -1, 0
	s_lshl_b32 s21, s79, 11
	s_ashr_i32 s89, s33, 31
	s_ashr_i32 s90, s2, 31
	v_and_b32_e32 v1, 32, v1
	s_add_u32 s36, s22, 0x13e000
	v_bitop3_b32 v2, v0, s25, v1 bitop3:0xde
	v_bitop3_b32 v220, v0, s26, v1 bitop3:0xde
	s_addc_u32 s37, s23, 0
	v_lshlrev_b32_e32 v0, 15, v9
	s_add_u32 s50, s22, 0x140000
	v_and_b32_e32 v0, 0xffff0000, v0
	s_addc_u32 s51, s23, 0
	s_lshl_b32 s24, s24, 2
	v_lshl_add_u32 v0, v10, 12, v0
	v_and_b32_e32 v1, 1, v9
	s_add_i32 s24, s24, 0
	v_lshl_or_b32 v0, v1, 6, v0
	s_add_i32 s91, s24, s21
	v_lshl_add_u32 v206, v11, 1, v0
	v_lshlrev_b32_e32 v0, 15, v12
	s_add_i32 s91, s91, 0x20000
	v_and_b32_e32 v0, 0xffff0000, v0
	s_waitcnt vmcnt(6)
	s_add_u32 s52, s22, 0xf142000
	v_lshl_add_u32 v0, v13, 12, v0
	v_and_b32_e32 v1, 1, v12
	s_addc_u32 s53, s23, 0
	v_lshl_or_b32 v0, v1, 6, v0
	s_add_i32 s93, 0, 0x10000
	s_add_i32 s94, 0, 0x14000
	v_mov_b32_e32 v207, v205
	v_lshl_add_u32 v208, v14, 1, v0
	v_mov_b32_e32 v209, v205
	v_mov_b64_e32 v[210:211], 0x5ff
	s_movk_i32 s92, 0xff
	v_add_u32_e32 v221, s93, v220
	v_add_u32_e32 v222, s94, v220
	v_add_u32_e32 v223, 0, v2
	s_mov_b32 s95, 0xbf40000
	s_lshl_b32 s96, s20, 2
	v_mov_b32_e32 v224, 0x358637bd
	s_movk_i32 s97, 0x1200
	s_movk_i32 s44, 0x1000
	s_movk_i32 s45, 0x3000
	s_movk_i32 s20, 0xdf
	s_movk_i32 s21, 0xef
	v_mov_b64_e32 v[212:213], 0x4f
	s_mov_b32 s24, 0
	s_barrier
	s_mov_b32 s101, 0
	s_branch .LBB0_126

; #define PG8_BAR __builtin_amdgcn_s_barrier()
; template <class Epi, class Sched, bool ALIGN_EPI = false, bool SP2 = false>
; __device__ __forceinline__ void gemm_phase(PG8_LAS unsigned char* lds, const Gemm g, const Sched& S, const Epi& E, const int wave_id_in) {
;     ...
;         if constexpr (!Epi::AFTER_DRAIN) { E(acc, cur, wr, wc, fr, fq); if constexpr (Epi::PREF) { if (has_next) E.prefetch(nxt, wid); } S.done(cur); }
;         if (!has_next) break;
;         if constexpr (Epi::CARRY) {
;             const float keep = (cur.br == 0) ? 1.0f : 0.0f;
; #pragma unroll
;             for (int a = 0; a < 2; ++a)
; #pragma unroll
;                 for (int b = 0; b < 2; ++b)
; #pragma unroll
;                     for (int m = 0; m < 4; ++m)
; #pragma unroll
;                         for (int n = 0; n < 2; ++n) acc[a][b][m][n] = acc[a][b][m][n] * keep;
;         } else {
; #pragma unroll
;         for (int a = 0; a < 2; ++a)
; #pragma unroll
;             for (int b = 0; b < 2; ++b)
; #pragma unroll
;                 for (int m = 0; m < 4; ++m)
; #pragma unroll
;                     for (int n = 0; n < 2; ++n) acc[a][b][m][n] = (f32x4){0.f, 0.f, 0.f, 0.f};
;         }
;         cur = nxt; cA = nA; cB = nB; ++ui;
;         if constexpr (ALIGN_EPI) { if (wr == 1) PG8_BAR; }
.LBB0_125:
	s_mov_b32 s101, 1
	s_andn2_b64 vcc, exec, s[6:7]
	s_mov_b32 s66, s54
	s_mov_b32 s64, s56
	s_mov_b64 s[68:69], s[62:63]
	s_mov_b64 s[6:7], s[60:61]
	s_cbranch_vccz .LBB0_211

;     __host__ __device__ bool next(int i, Unit& u) const { const long L = (long)i * G + c; if (L >= maxL) return false; return unit_of(L, u); }
;     __device__ __forceinline__ const char* a_base(const Gemm& g, const Unit& u, size_t tstep) const { return (const char*)g.A + (size_t)u.pm * tstep; }
;     __device__ __forceinline__ const char* b_base(const Gemm& g, const Unit& u, size_t tstep) const { return (const char*)g.Bt + (size_t)u.pn * tstep; }
; #define PG8_STAGE(bufoff, gbase, voff) do { _Pragma("unroll") for (int _i = 0; _i < 2; ++_i) \
;         __builtin_amdgcn_global_load_lds((const unsigned*)((const char*)(gbase) + (voff)[_i]), (PG8_LAS unsigned*)(lds + (bufoff) + ldsw + _i * 8192), 16, 0, 0); } while (0)
; #define PG8_WAIT_V(n) asm volatile("s_waitcnt vmcnt(" #n ")" ::: "memory")
; #define PG8_WAIT_L(n) asm volatile("s_waitcnt lgkmcnt(" #n ")" ::: "memory")
; template <class Epi, class Sched, bool ALIGN_EPI = false, bool SP2 = false>
; __device__ __forceinline__ void gemm_phase(PG8_LAS unsigned char* lds, const Gemm g, const Sched& S, const Epi& E, const int wave_id_in) {
;     ...
;         const bool has_next = S.next(ui + 1, nxt);
;         const char* nA = has_next ? S.a_base(g, nxt, tstep) : cA; const char* nB = has_next ? S.b_base(g, nxt, tstep) : cB;
;         for (int t = 0; t < nt; t += 2) {
;             const bool last = (t == nt - 2);
;             const char* a1 = cA + (size_t)(t + 1) * kstep;
;             const char* a2 = last ? nA : cA + (size_t)(t + 2) * kstep; const char* b2 = last ? nB : cB + (size_t)(t + 2) * kstep;
;             const char* a3 = a2 + kstep; const char* b3 = b2 + kstep;
;             if (last && has_next) S.a_ready(nxt);
;             if constexpr (SP2) {
;             PG8_LDB(B0, 0, 0); PG8_LDB(B1, 0, 1); PG8_SCHED; PG8_LDA(At, 0, 0); PG8_STAGE(PG8_SA(1, 1), a1 + hstep, voffA);
;             PG8_WAIT_V(8); PG8_WAIT_L(0); PG8_BAR; __builtin_amdgcn_s_setprio(1); PG8_MMA(0, 0, At, B0); PG8_MMA(0, 1, At, B1); __builtin_amdgcn_s_setprio(0); PG8_BAR; PG8_SCHED;
;             PG8_LDA(At, 0, 1); PG8_STAGE(PG8_SB(0, 0), b2, voffB); PG8_STAGE(PG8_SB(0, 1), b2 + hstep, voffB); PG8_STAGE(PG8_SA(0, 0), a2, voffA);
;             PG8_WAIT_V(8); PG8_WAIT_L(0); PG8_BAR; __builtin_amdgcn_s_setprio(1); PG8_MMA(1, 0, At, B0); PG8_MMA(1, 1, At, B1); __builtin_amdgcn_s_setprio(0); PG8_BAR; PG8_SCHED;
.LBB0_131:
	s_ashr_i32 s57, s56, 31
	s_lshl_b64 s[38:39], s[56:57], 20
	s_add_u32 s60, s47, s38
	s_addc_u32 s61, s49, s39
	s_and_b64 s[38:39], s[58:59], exec
	s_cselect_b32 s25, s61, s7
	s_cselect_b32 s26, s60, s6
	s_ashr_i32 s55, s54, 31
	s_lshl_b64 s[38:39], s[54:55], 20
	s_add_u32 s62, s75, s38
	s_addc_u32 s63, s78, s39
	s_and_b64 s[38:39], s[58:59], exec
	s_cselect_b32 s38, s63, s69
	s_cselect_b32 s39, s62, s68
	s_add_u32 s6, s6, 0x80080
	s_addc_u32 s7, s7, 0
	s_add_u32 s42, s68, 0x100
	s_addc_u32 s43, s69, 0
	s_mov_b32 s55, -2
	ds_read_b128 v[128:131], v221
	ds_read_b128 v[132:135], v221 offset:1024
	ds_read_b128 v[136:139], v221 offset:2048
	ds_read_b128 v[140:143], v221 offset:3072
	ds_read_b128 v[144:147], v222
	ds_read_b128 v[148:151], v222 offset:1024
	ds_read_b128 v[152:155], v222 offset:2048
	ds_read_b128 v[156:159], v222 offset:3072
	s_add_u32 s40, s6, 0xfff80080
	s_addc_u32 s41, s7, -1
	s_cmp_eq_u32 s55, 28
	s_cselect_b32 s71, s25, s41
	s_cselect_b32 s70, s26, s40
	s_cselect_b32 s69, s38, s43
	s_cselect_b32 s68, s39, s42
	v_lshl_add_u64 v[192:193], s[6:7], 0, v[206:207]
	s_add_i32 m0, s65, 0xc000
	ds_read_b128 v[160:163], v223
	ds_read_b128 v[164:167], v223 offset:1024
	ds_read_b128 v[168:171], v223 offset:2048
	ds_read_b128 v[172:175], v223 offset:3072
	ds_read_b128 v[176:179], v223 offset:4096
	ds_read_b128 v[180:183], v223 offset:5120
	ds_read_b128 v[184:187], v223 offset:6144
	ds_read_b128 v[188:191], v223 offset:7168
	global_load_lds_dwordx4 v[192:193], off
	v_lshl_add_u64 v[192:193], s[6:7], 0, v[208:209]
	s_add_i32 m0, s65, 0xe000
	s_nop 0
	global_load_lds_dwordx4 v[192:193], off
	s_cmp_lg_u32 s101, 0
	s_cbranch_scc1 .Lpw_inproj_0_r
	s_waitcnt vmcnt(8)
	s_branch .Lpw_inproj_0_j
.Lpw_inproj_0_r:
	s_waitcnt vmcnt(38)
.Lpw_inproj_0_j:
	s_waitcnt lgkmcnt(0)
	s_barrier
	s_setprio 1
	s_waitcnt lgkmcnt(0)
	v_mfma_f32_16x16x32_bf16 v[124:127], v[128:131], v[160:163], 0
	v_mfma_f32_16x16x32_bf16 v[120:123], v[136:139], v[160:163], 0
	v_mfma_f32_16x16x32_bf16 v[108:111], v[128:131], v[168:171], 0
	v_mfma_f32_16x16x32_bf16 v[104:107], v[136:139], v[168:171], 0
	v_mfma_f32_16x16x32_bf16 v[92:95], v[128:131], v[176:179], 0
	v_mfma_f32_16x16x32_bf16 v[88:91], v[136:139], v[176:179], 0
	v_mfma_f32_16x16x32_bf16 v[76:79], v[128:131], v[184:187], 0
	v_mfma_f32_16x16x32_bf16 v[72:75], v[136:139], v[184:187], 0
	v_mfma_f32_16x16x32_bf16 v[116:119], v[144:147], v[160:163], 0
	v_mfma_f32_16x16x32_bf16 v[112:115], v[152:155], v[160:163], 0
	v_mfma_f32_16x16x32_bf16 v[100:103], v[144:147], v[168:171], 0
	v_mfma_f32_16x16x32_bf16 v[96:99], v[152:155], v[168:171], 0
	v_mfma_f32_16x16x32_bf16 v[84:87], v[144:147], v[176:179], 0
	v_mfma_f32_16x16x32_bf16 v[80:83], v[152:155], v[176:179], 0
	v_mfma_f32_16x16x32_bf16 v[68:71], v[144:147], v[184:187], 0
	v_mfma_f32_16x16x32_bf16 v[64:67], v[152:155], v[184:187], 0
	v_mfma_f32_16x16x32_bf16 v[124:127], v[132:135], v[164:167], v[124:127]
	v_mfma_f32_16x16x32_bf16 v[120:123], v[140:143], v[164:167], v[120:123]
	v_mfma_f32_16x16x32_bf16 v[108:111], v[132:135], v[172:175], v[108:111]
	v_mfma_f32_16x16x32_bf16 v[104:107], v[140:143], v[172:175], v[104:107]
	v_mfma_f32_16x16x32_bf16 v[92:95], v[132:135], v[180:183], v[92:95]
	v_mfma_f32_16x16x32_bf16 v[88:91], v[140:143], v[180:183], v[88:91]
	v_mfma_f32_16x16x32_bf16 v[76:79], v[132:135], v[188:191], v[76:79]
	v_mfma_f32_16x16x32_bf16 v[72:75], v[140:143], v[188:191], v[72:75]
	v_mfma_f32_16x16x32_bf16 v[116:119], v[148:151], v[164:167], v[116:119]
	v_mfma_f32_16x16x32_bf16 v[112:115], v[156:159], v[164:167], v[112:115]
	v_mfma_f32_16x16x32_bf16 v[100:103], v[148:151], v[172:175], v[100:103]
	v_mfma_f32_16x16x32_bf16 v[96:99], v[156:159], v[172:175], v[96:99]
	v_mfma_f32_16x16x32_bf16 v[84:87], v[148:151], v[180:183], v[84:87]
	v_mfma_f32_16x16x32_bf16 v[80:83], v[156:159], v[180:183], v[80:83]
	v_mfma_f32_16x16x32_bf16 v[68:71], v[148:151], v[188:191], v[68:71]
	v_mfma_f32_16x16x32_bf16 v[64:67], v[156:159], v[188:191], v[64:67]
	s_setprio 0
	s_barrier
	s_add_i32 s40, s93, s80
	v_lshl_add_u64 v[192:193], s[68:69], 0, v[200:201]
	s_mov_b32 m0, s40
	ds_read_b128 v[160:163], v223 offset:16384
	ds_read_b128 v[164:167], v223 offset:17408
	ds_read_b128 v[168:171], v223 offset:18432
	ds_read_b128 v[172:175], v223 offset:19456
	ds_read_b128 v[176:179], v223 offset:20480
	ds_read_b128 v[180:183], v223 offset:21504
	ds_read_b128 v[184:187], v223 offset:22528
	ds_read_b128 v[188:191], v223 offset:23552
	global_load_lds_dwordx4 v[192:193], off
	s_add_i32 m0, s40, 0x2000
	s_add_u32 s72, s68, 0x80000
	v_lshl_add_u64 v[194:195], s[68:69], 0, v[202:203]
	s_addc_u32 s73, s69, 0
	s_add_i32 s40, s94, s80
	global_load_lds_dwordx4 v[194:195], off
	v_lshl_add_u64 v[196:197], s[72:73], 0, v[200:201]
	s_mov_b32 m0, s40
	v_lshl_add_u64 v[198:199], s[70:71], 0, v[202:203]
	global_load_lds_dwordx4 v[196:197], off
	v_lshl_add_u64 v[196:197], s[72:73], 0, v[202:203]
	s_add_i32 m0, s40, 0x2000
	s_nop 0
	global_load_lds_dwordx4 v[196:197], off
	v_lshl_add_u64 v[196:197], s[70:71], 0, v[200:201]
	s_mov_b32 m0, s65
	s_nop 0
	global_load_lds_dwordx4 v[196:197], off
	s_mov_b32 m0, s67
	s_nop 0
	global_load_lds_dwordx4 v[198:199], off
	s_cmp_lg_u32 s101, 0
	s_cbranch_scc1 .Lpw_inproj_1_r
	s_waitcnt vmcnt(8)
	s_branch .Lpw_inproj_1_j

; #define PG8_STAGE(bufoff, gbase, voff) do { _Pragma("unroll") for (int _i = 0; _i < 2; ++_i) \
;         __builtin_amdgcn_global_load_lds((const unsigned*)((const char*)(gbase) + (voff)[_i]), (PG8_LAS unsigned*)(lds + (bufoff) + ldsw + _i * 8192), 16, 0, 0); } while (0)
; #define PG8_LDA(dst, b, h) do { _Pragma("unroll") for (int m = 0; m < 4; ++m) _Pragma("unroll") for (int k = 0; k < 2; ++k) dst[m][k] = *(const PG8_LAS bf16x8*)(lds + PG8_SA(b, h) + aoff + m * 2048 + k * 1024); } while (0)
; #define PG8_LDB(dst, b, h) do { _Pragma("unroll") for (int n = 0; n < 2; ++n) _Pragma("unroll") for (int k = 0; k < 2; ++k) dst[n][k] = *(const PG8_LAS bf16x8*)(lds + PG8_SB(b, h) + boff + n * 2048 + k * 1024); } while (0)
; #define PG8_MMA(ai, bj, At, Bt) do { _Pragma("unroll") for (int m = 0; m < 4; ++m) _Pragma("unroll") for (int n = 0; n < 2; ++n) _Pragma("unroll") for (int k = 0; k < 2; ++k) \
;         acc[ai][bj][m][n] = __builtin_amdgcn_mfma_f32_16x16x32_bf16(Bt[n][k], At[m][k], acc[ai][bj][m][n], 0, 0, 0); } while (0)
; #define PG8_WAIT_V(n) asm volatile("s_waitcnt vmcnt(" #n ")" ::: "memory")
; #define PG8_WAIT_L(n) asm volatile("s_waitcnt lgkmcnt(" #n ")" ::: "memory")
; #define PG8_BAR __builtin_amdgcn_s_barrier()
; #define PG8_SCHED __builtin_amdgcn_sched_barrier(0)
; template <class Epi, class Sched, bool ALIGN_EPI = false, bool SP2 = false>
; __device__ __forceinline__ void gemm_phase(PG8_LAS unsigned char* lds, const Gemm g, const Sched& S, const Epi& E, const int wave_id_in) {
;     ...
;             PG8_WAIT_V(8); PG8_WAIT_L(0); PG8_BAR; __builtin_amdgcn_s_setprio(1); PG8_MMA(1, 0, At, B0); PG8_MMA(1, 1, At, B1); __builtin_amdgcn_s_setprio(0); PG8_BAR; PG8_SCHED;
;             PG8_LDB(B0, 1, 0); PG8_LDB(B1, 1, 1); PG8_SCHED; PG8_LDA(At, 1, 0); PG8_STAGE(PG8_SA(0, 1), a2 + hstep, voffA);
;             PG8_WAIT_V(8); PG8_WAIT_L(0); PG8_BAR; __builtin_amdgcn_s_setprio(1); PG8_MMA(0, 0, At, B0); PG8_MMA(0, 1, At, B1); __builtin_amdgcn_s_setprio(0); PG8_BAR; PG8_SCHED;
.Lpw_inproj_1_j:
	s_waitcnt lgkmcnt(0)
	s_barrier
	s_setprio 1
	s_waitcnt lgkmcnt(0)
	v_mfma_f32_16x16x32_bf16 v[60:63], v[128:131], v[160:163], 0
	v_mfma_f32_16x16x32_bf16 v[56:59], v[136:139], v[160:163], 0
	v_mfma_f32_16x16x32_bf16 v[44:47], v[128:131], v[168:171], 0
	v_mfma_f32_16x16x32_bf16 v[40:43], v[136:139], v[168:171], 0
	v_mfma_f32_16x16x32_bf16 v[28:31], v[128:131], v[176:179], 0
	v_mfma_f32_16x16x32_bf16 v[24:27], v[136:139], v[176:179], 0
	v_mfma_f32_16x16x32_bf16 v[12:15], v[128:131], v[184:187], 0
	v_mfma_f32_16x16x32_bf16 v[8:11], v[136:139], v[184:187], 0
	v_mfma_f32_16x16x32_bf16 v[52:55], v[144:147], v[160:163], 0
	v_mfma_f32_16x16x32_bf16 v[48:51], v[152:155], v[160:163], 0
	v_mfma_f32_16x16x32_bf16 v[36:39], v[144:147], v[168:171], 0
	v_mfma_f32_16x16x32_bf16 v[32:35], v[152:155], v[168:171], 0
	v_mfma_f32_16x16x32_bf16 v[20:23], v[144:147], v[176:179], 0
	v_mfma_f32_16x16x32_bf16 v[16:19], v[152:155], v[176:179], 0
	v_mfma_f32_16x16x32_bf16 v[4:7], v[144:147], v[184:187], 0
	v_mfma_f32_16x16x32_bf16 v[0:3], v[152:155], v[184:187], 0
	v_mfma_f32_16x16x32_bf16 v[60:63], v[132:135], v[164:167], v[60:63]
	v_mfma_f32_16x16x32_bf16 v[56:59], v[140:143], v[164:167], v[56:59]
	v_mfma_f32_16x16x32_bf16 v[44:47], v[132:135], v[172:175], v[44:47]
	v_mfma_f32_16x16x32_bf16 v[40:43], v[140:143], v[172:175], v[40:43]
	v_mfma_f32_16x16x32_bf16 v[28:31], v[132:135], v[180:183], v[28:31]
	v_mfma_f32_16x16x32_bf16 v[24:27], v[140:143], v[180:183], v[24:27]
	v_mfma_f32_16x16x32_bf16 v[12:15], v[132:135], v[188:191], v[12:15]
	v_mfma_f32_16x16x32_bf16 v[8:11], v[140:143], v[188:191], v[8:11]
	v_mfma_f32_16x16x32_bf16 v[52:55], v[148:151], v[164:167], v[52:55]
	v_mfma_f32_16x16x32_bf16 v[48:51], v[156:159], v[164:167], v[48:51]
	v_mfma_f32_16x16x32_bf16 v[36:39], v[148:151], v[172:175], v[36:39]
	v_mfma_f32_16x16x32_bf16 v[32:35], v[156:159], v[172:175], v[32:35]
	v_mfma_f32_16x16x32_bf16 v[20:23], v[148:151], v[180:183], v[20:23]
	v_mfma_f32_16x16x32_bf16 v[16:19], v[156:159], v[180:183], v[16:19]
	v_mfma_f32_16x16x32_bf16 v[4:7], v[148:151], v[188:191], v[4:7]
	v_mfma_f32_16x16x32_bf16 v[0:3], v[156:159], v[188:191], v[0:3]
	s_setprio 0
	s_barrier
	s_add_i32 s40, 0, 0x18000
	s_add_i32 s41, 0, 0x1c000
	v_add_u32_e32 v140, s40, v220
	v_add_u32_e32 v156, s41, v220
	ds_read_b128 v[128:131], v140
	ds_read_b128 v[132:135], v140 offset:1024
	ds_read_b128 v[136:139], v140 offset:2048
	ds_read_b128 v[140:143], v140 offset:3072
	ds_read_b128 v[144:147], v156
	ds_read_b128 v[148:151], v156 offset:1024
	ds_read_b128 v[152:155], v156 offset:2048
	ds_read_b128 v[156:159], v156 offset:3072
	s_add_u32 s70, s70, 0x80000
	s_addc_u32 s71, s71, 0
	s_mov_b32 m0, s81
	v_lshl_add_u64 v[214:215], s[70:71], 0, v[200:201]
	ds_read_b128 v[160:163], v223 offset:32768
	ds_read_b128 v[164:167], v223 offset:33792
	ds_read_b128 v[168:171], v223 offset:34816
	ds_read_b128 v[172:175], v223 offset:35840
	ds_read_b128 v[176:179], v223 offset:36864
	ds_read_b128 v[180:183], v223 offset:37888
	ds_read_b128 v[184:187], v223 offset:38912
	ds_read_b128 v[188:191], v223 offset:39936
	global_load_lds_dwordx4 v[214:215], off
	v_lshl_add_u64 v[214:215], s[70:71], 0, v[202:203]
	s_mov_b32 m0, s82
	s_nop 0
	global_load_lds_dwordx4 v[214:215], off
	s_waitcnt vmcnt(8)
	s_waitcnt lgkmcnt(0)
	s_barrier
	s_setprio 1
	s_waitcnt lgkmcnt(0)
	v_mfma_f32_16x16x32_bf16 v[124:127], v[128:131], v[160:163], v[124:127]
	v_mfma_f32_16x16x32_bf16 v[120:123], v[136:139], v[160:163], v[120:123]
	v_mfma_f32_16x16x32_bf16 v[108:111], v[128:131], v[168:171], v[108:111]
	v_mfma_f32_16x16x32_bf16 v[104:107], v[136:139], v[168:171], v[104:107]
	v_mfma_f32_16x16x32_bf16 v[92:95], v[128:131], v[176:179], v[92:95]
	v_mfma_f32_16x16x32_bf16 v[88:91], v[136:139], v[176:179], v[88:91]
	v_mfma_f32_16x16x32_bf16 v[76:79], v[128:131], v[184:187], v[76:79]
	v_mfma_f32_16x16x32_bf16 v[72:75], v[136:139], v[184:187], v[72:75]
	v_mfma_f32_16x16x32_bf16 v[116:119], v[144:147], v[160:163], v[116:119]
	v_mfma_f32_16x16x32_bf16 v[112:115], v[152:155], v[160:163], v[112:115]
	v_mfma_f32_16x16x32_bf16 v[100:103], v[144:147], v[168:171], v[100:103]
	v_mfma_f32_16x16x32_bf16 v[96:99], v[152:155], v[168:171], v[96:99]
	v_mfma_f32_16x16x32_bf16 v[84:87], v[144:147], v[176:179], v[84:87]
	v_mfma_f32_16x16x32_bf16 v[80:83], v[152:155], v[176:179], v[80:83]
	v_mfma_f32_16x16x32_bf16 v[68:71], v[144:147], v[184:187], v[68:71]
	v_mfma_f32_16x16x32_bf16 v[64:67], v[152:155], v[184:187], v[64:67]
	v_mfma_f32_16x16x32_bf16 v[124:127], v[132:135], v[164:167], v[124:127]
	v_mfma_f32_16x16x32_bf16 v[120:123], v[140:143], v[164:167], v[120:123]
	v_mfma_f32_16x16x32_bf16 v[108:111], v[132:135], v[172:175], v[108:111]
	v_mfma_f32_16x16x32_bf16 v[104:107], v[140:143], v[172:175], v[104:107]
	v_mfma_f32_16x16x32_bf16 v[92:95], v[132:135], v[180:183], v[92:95]
	v_mfma_f32_16x16x32_bf16 v[88:91], v[140:143], v[180:183], v[88:91]
	v_mfma_f32_16x16x32_bf16 v[76:79], v[132:135], v[188:191], v[76:79]
	v_mfma_f32_16x16x32_bf16 v[72:75], v[140:143], v[188:191], v[72:75]
	v_mfma_f32_16x16x32_bf16 v[116:119], v[148:151], v[164:167], v[116:119]
	v_mfma_f32_16x16x32_bf16 v[112:115], v[156:159], v[164:167], v[112:115]
	v_mfma_f32_16x16x32_bf16 v[100:103], v[148:151], v[172:175], v[100:103]
	v_mfma_f32_16x16x32_bf16 v[96:99], v[156:159], v[172:175], v[96:99]
	v_mfma_f32_16x16x32_bf16 v[84:87], v[148:151], v[180:183], v[84:87]
	v_mfma_f32_16x16x32_bf16 v[80:83], v[156:159], v[180:183], v[80:83]
	v_mfma_f32_16x16x32_bf16 v[68:71], v[148:151], v[188:191], v[68:71]
	v_mfma_f32_16x16x32_bf16 v[64:67], v[156:159], v[188:191], v[64:67]
	s_setprio 0
	s_barrier
; #define PG8_STAGE(bufoff, gbase, voff) do { _Pragma("unroll") for (int _i = 0; _i < 2; ++_i) \
;         __builtin_amdgcn_global_load_lds((const unsigned*)((const char*)(gbase) + (voff)[_i]), (PG8_LAS unsigned*)(lds + (bufoff) + ldsw + _i * 8192), 16, 0, 0); } while (0)
; #define PG8_LDA(dst, b, h) do { _Pragma("unroll") for (int m = 0; m < 4; ++m) _Pragma("unroll") for (int k = 0; k < 2; ++k) dst[m][k] = *(const PG8_LAS bf16x8*)(lds + PG8_SA(b, h) + aoff + m * 2048 + k * 1024); } while (0)
; #define PG8_MMA(ai, bj, At, Bt) do { _Pragma("unroll") for (int m = 0; m < 4; ++m) _Pragma("unroll") for (int n = 0; n < 2; ++n) _Pragma("unroll") for (int k = 0; k < 2; ++k) \
;         acc[ai][bj][m][n] = __builtin_amdgcn_mfma_f32_16x16x32_bf16(Bt[n][k], At[m][k], acc[ai][bj][m][n], 0, 0, 0); } while (0)
; #define PG8_WAIT_V(n) asm volatile("s_waitcnt vmcnt(" #n ")" ::: "memory")
; #define PG8_WAIT_L(n) asm volatile("s_waitcnt lgkmcnt(" #n ")" ::: "memory")
; #define PG8_BAR __builtin_amdgcn_s_barrier()
; #define PG8_SCHED __builtin_amdgcn_sched_barrier(0)
; template <class Epi, class Sched, bool ALIGN_EPI = false, bool SP2 = false>
; __device__ __forceinline__ void gemm_phase(PG8_LAS unsigned char* lds, const Gemm g, const Sched& S, const Epi& E, const int wave_id_in) {
;     ...
;             PG8_LDA(At, 1, 1); PG8_STAGE(PG8_SB(1, 0), b3, voffB); PG8_STAGE(PG8_SB(1, 1), b3 + hstep, voffB); PG8_STAGE(PG8_SA(1, 0), a3, voffA);
;             PG8_WAIT_V(8); PG8_WAIT_L(0); PG8_BAR; __builtin_amdgcn_s_setprio(1); PG8_MMA(1, 0, At, B0); PG8_MMA(1, 1, At, B1); __builtin_amdgcn_s_setprio(0); PG8_BAR; PG8_SCHED;
	s_add_i32 s40, s40, s80
	v_lshl_add_u64 v[192:193], v[192:193], 0, s[30:31]
	s_mov_b32 m0, s40
	ds_read_b128 v[160:163], v223 offset:49152
	ds_read_b128 v[164:167], v223 offset:50176
	ds_read_b128 v[168:171], v223 offset:51200
	ds_read_b128 v[172:175], v223 offset:52224
	ds_read_b128 v[176:179], v223 offset:53248
	ds_read_b128 v[180:183], v223 offset:54272
	ds_read_b128 v[184:187], v223 offset:55296
	ds_read_b128 v[188:191], v223 offset:56320
	global_load_lds_dwordx4 v[192:193], off
	s_add_i32 m0, s40, 0x2000
	s_add_u32 s68, s68, 0x80080
	v_lshl_add_u64 v[192:193], v[194:195], 0, s[30:31]
	s_addc_u32 s69, s69, 0
	s_add_i32 s40, s41, s80
	global_load_lds_dwordx4 v[192:193], off
	v_lshl_add_u64 v[192:193], s[68:69], 0, v[200:201]
	s_mov_b32 m0, s40
	s_nop 0
	global_load_lds_dwordx4 v[192:193], off
	v_lshl_add_u64 v[192:193], s[68:69], 0, v[202:203]
	s_add_i32 m0, s40, 0x2000
	s_nop 0
	global_load_lds_dwordx4 v[192:193], off
	v_lshl_add_u64 v[192:193], v[196:197], 0, s[30:31]
	s_mov_b32 m0, s86
	s_nop 0
	global_load_lds_dwordx4 v[192:193], off
	v_lshl_add_u64 v[192:193], v[198:199], 0, s[30:31]
	s_mov_b32 m0, s87
	s_nop 0
	global_load_lds_dwordx4 v[192:193], off
	s_waitcnt vmcnt(8)
	s_waitcnt lgkmcnt(0)
	s_barrier
	s_setprio 1
	s_waitcnt lgkmcnt(0)
	v_mfma_f32_16x16x32_bf16 v[60:63], v[128:131], v[160:163], v[60:63]
	v_mfma_f32_16x16x32_bf16 v[56:59], v[136:139], v[160:163], v[56:59]
	v_mfma_f32_16x16x32_bf16 v[44:47], v[128:131], v[168:171], v[44:47]
	v_mfma_f32_16x16x32_bf16 v[40:43], v[136:139], v[168:171], v[40:43]
	v_mfma_f32_16x16x32_bf16 v[28:31], v[128:131], v[176:179], v[28:31]
	v_mfma_f32_16x16x32_bf16 v[24:27], v[136:139], v[176:179], v[24:27]
	v_mfma_f32_16x16x32_bf16 v[12:15], v[128:131], v[184:187], v[12:15]
	v_mfma_f32_16x16x32_bf16 v[8:11], v[136:139], v[184:187], v[8:11]
	v_mfma_f32_16x16x32_bf16 v[52:55], v[144:147], v[160:163], v[52:55]
	v_mfma_f32_16x16x32_bf16 v[48:51], v[152:155], v[160:163], v[48:51]
	v_mfma_f32_16x16x32_bf16 v[36:39], v[144:147], v[168:171], v[36:39]
	v_mfma_f32_16x16x32_bf16 v[32:35], v[152:155], v[168:171], v[32:35]
	v_mfma_f32_16x16x32_bf16 v[20:23], v[144:147], v[176:179], v[20:23]
	v_mfma_f32_16x16x32_bf16 v[16:19], v[152:155], v[176:179], v[16:19]
	v_mfma_f32_16x16x32_bf16 v[4:7], v[144:147], v[184:187], v[4:7]
	v_mfma_f32_16x16x32_bf16 v[0:3], v[152:155], v[184:187], v[0:3]
	v_mfma_f32_16x16x32_bf16 v[60:63], v[132:135], v[164:167], v[60:63]
	v_mfma_f32_16x16x32_bf16 v[56:59], v[140:143], v[164:167], v[56:59]
	v_mfma_f32_16x16x32_bf16 v[44:47], v[132:135], v[172:175], v[44:47]
	v_mfma_f32_16x16x32_bf16 v[40:43], v[140:143], v[172:175], v[40:43]
	v_mfma_f32_16x16x32_bf16 v[28:31], v[132:135], v[180:183], v[28:31]
	v_mfma_f32_16x16x32_bf16 v[24:27], v[140:143], v[180:183], v[24:27]
	v_mfma_f32_16x16x32_bf16 v[12:15], v[132:135], v[188:191], v[12:15]
	v_mfma_f32_16x16x32_bf16 v[8:11], v[140:143], v[188:191], v[8:11]
	v_mfma_f32_16x16x32_bf16 v[52:55], v[148:151], v[164:167], v[52:55]
	v_mfma_f32_16x16x32_bf16 v[48:51], v[156:159], v[164:167], v[48:51]
	v_mfma_f32_16x16x32_bf16 v[36:39], v[148:151], v[172:175], v[36:39]
	v_mfma_f32_16x16x32_bf16 v[32:35], v[156:159], v[172:175], v[32:35]
	v_mfma_f32_16x16x32_bf16 v[20:23], v[148:151], v[180:183], v[20:23]
	v_mfma_f32_16x16x32_bf16 v[16:19], v[156:159], v[180:183], v[16:19]
	v_mfma_f32_16x16x32_bf16 v[4:7], v[148:151], v[188:191], v[4:7]
	v_mfma_f32_16x16x32_bf16 v[0:3], v[156:159], v[188:191], v[0:3]
	s_setprio 0
	s_barrier
	s_add_i32 s55, s55, 2
	s_add_u32 s6, s6, 0x100
	s_addc_u32 s7, s7, 0
	s_add_u32 s42, s42, 0x100
	s_addc_u32 s43, s43, 0
	s_cmp_gt_u32 s55, 29
	s_cbranch_scc0 .LBB0_132
	s_branch .Lpeel_exit_inproj

; __device__ __forceinline__ int tid_of(int wave_id) { int t = wave_id * 64 + lane_id(); asm volatile("" : "+v"(t)); return t; }
; #define PG8_STAGE(bufoff, gbase, voff) do { _Pragma("unroll") for (int _i = 0; _i < 2; ++_i) \
;         __builtin_amdgcn_global_load_lds((const unsigned*)((const char*)(gbase) + (voff)[_i]), (PG8_LAS unsigned*)(lds + (bufoff) + ldsw + _i * 8192), 16, 0, 0); } while (0)
; #define PG8_WAIT_V(n) asm volatile("s_waitcnt vmcnt(" #n ")" ::: "memory")
; #define PG8_BAR __builtin_amdgcn_s_barrier()
; template <class Epi, class Sched, bool ALIGN_EPI = false, bool SP2 = false>
; __device__ __forceinline__ void gemm_phase(PG8_LAS unsigned char* lds, const Gemm g, const Sched& S, const Epi& E, const int wave_id_in) {
;     int tid_o = tid_of(wave_id_in);
;     const int tid = tid_o, wid = __builtin_amdgcn_readfirstlane(tid >> 6), lane = tid & 63, wr = wid >> 2, wc = wid & 3, fr = lane & 15, fq = lane >> 4;
;     const int K = g.K, nt = K / BK;
;     unsigned voffA[2], voffB[2];
; #pragma unroll
;     for (int i = 0; i < 2; ++i) { int R, C; stage_rc(tid * 16 + i * 8192, R, C); const int Rb = Epi::PERM ? ((R & ~31) + perm32(R & 31)) : R;
;         voffA[i] = (unsigned)(R * K + C) * 2u; voffB[i] = (unsigned)(Rb * K + C) * 2u; }
;     const size_t kstep = (size_t)(BK * 2);
;     const size_t hstep = (size_t)HALF * K * 2;
;     const size_t tstep = 2 * hstep;
;     const unsigned ldsw = (unsigned)wid * 1024u;
;     const int aoff = lds_byte(wr * 64 + fr, fq * 8), boff = lds_byte(wc * 32 + fr, fq * 8);
;     ...
;         PG8_STAGE(PG8_SB(0, 0), cB, voffB); PG8_STAGE(PG8_SB(0, 1), cB + hstep, voffB); PG8_STAGE(PG8_SA(0, 0), cA, voffA); PG8_STAGE(PG8_SA(0, 1), cA + hstep, voffA);
;         if (wr == 1) PG8_BAR;
;         PG8_WAIT_V(2); PG8_BAR;
;         PG8_STAGE(PG8_SB(1, 0), cB + kstep, voffB); PG8_STAGE(PG8_SA(1, 0), cA + kstep, voffA); PG8_STAGE(PG8_SB(1, 1), cB + hstep + kstep, voffB);
;         PG8_WAIT_V(6); PG8_BAR;
.LBB0_813:
	s_lshl_b32 s9, s28, 5
	s_mov_b64 s[34:35], 0x80
	s_and_b32 s86, s9, 0x60
	s_add_i32 m0, s81, 0x18000
	v_lshl_add_u64 v[6:7], v[6:7], 0, s[34:35]
	s_lshl_b32 s85, s6, 6
	s_lshl_b32 s7, s6, 13
	s_lshl_b32 s9, s86, 7
	s_waitcnt vmcnt(2)
	s_barrier
	global_load_lds_dwordx4 v[6:7], off
	v_lshl_add_u64 v[4:5], v[4:5], 0, s[34:35]
	s_add_i32 m0, s81, 0x1a000
	s_add_i32 s87, s81, 0x8000
	s_add_i32 s88, s81, 0xa000
	global_load_lds_dwordx4 v[4:5], off
	v_lshl_add_u64 v[0:1], v[0:1], 0, s[34:35]
	s_mov_b32 m0, s87
	s_add_u32 s36, s12, 0x80080
	global_load_lds_dwordx4 v[0:1], off
	v_lshl_add_u64 v[0:1], v[2:3], 0, s[34:35]
	s_mov_b32 m0, s88
	s_addc_u32 s37, s13, 0
	global_load_lds_dwordx4 v[0:1], off
	s_add_i32 m0, s81, 0x1c000
	v_lshl_add_u64 v[0:1], s[36:37], 0, v[186:187]
	global_load_lds_dwordx4 v[0:1], off
	v_lshl_add_u64 v[0:1], s[36:37], 0, v[190:191]
	s_add_i32 m0, s81, 0x1e000
	s_movk_i32 s27, 0x3c0
	global_load_lds_dwordx4 v[0:1], off
	v_and_b32_e32 v0, 48, v8
	v_lshlrev_b32_e32 v1, 6, v8
	v_and_or_b32 v0, v1, s27, v0
	v_lshlrev_b32_e32 v1, 2, v8
	v_and_b32_e32 v1, 32, v1
	s_cmpk_lt_u32 s5, 0x100
	v_bitop3_b32 v2, v0, s7, v1 bitop3:0xde
	s_cselect_b64 s[36:37], -1, 0
	s_and_b32 s7, s5, 0xffffff00
	s_lshl_b32 s89, s6, 10
	s_cmp_gt_i32 s6, 0
	s_cselect_b64 s[46:47], -1, 0
	s_cmp_lt_i32 s6, 3
	s_cselect_b64 s[48:49], -1, 0
	s_cmp_gt_i32 s6, -2
	s_cselect_b64 s[50:51], -1, 0
	s_cmp_lt_i32 s6, 1
	s_cselect_b64 s[52:53], -1, 0
	s_cmp_lt_u32 s5, 64
	s_cselect_b64 s[54:55], -1, 0
	s_ashr_i32 s90, s33, 31
	s_ashr_i32 s91, s2, 31
	s_min_u32 s28, s4, 0x580
	s_add_u32 s56, s14, 0x14342000
	s_addc_u32 s57, s15, 0
	s_add_i32 s92, s7, 0
	s_add_i32 s92, s92, 0x21400
	s_add_u32 s93, s14, 0x5342000
	s_addc_u32 s94, s15, 0
	s_add_u32 s58, s16, 0x5800
	v_bitop3_b32 v220, s9, v0, v1 bitop3:0xf6
	s_addc_u32 s59, s17, 0
	v_lshlrev_b32_e32 v0, 15, v9
	s_add_u32 s60, s16, 0xb000
	v_and_b32_e32 v0, 0xffff0000, v0
	s_addc_u32 s61, s17, 0
	s_add_i32 s42, s89, 0
	v_lshl_add_u32 v0, v10, 12, v0
	v_and_b32_e32 v1, 1, v9
	s_add_i32 s95, s42, 0x20000
	s_add_i32 s96, s42, 0x20800
	s_add_i32 s97, s42, 0x1fe00
	s_add_i32 s42, s42, 0x20600
	v_lshl_or_b32 v0, v1, 6, v0
	s_add_u32 s62, s14, 0x10000
	v_lshl_add_u32 v194, v11, 1, v0
	v_lshlrev_b32_e32 v0, 15, v12
	s_addc_u32 s63, s15, 0
	v_and_b32_e32 v0, 0xffff0000, v0
	s_waitcnt vmcnt(6)
	s_add_u32 s43, s14, 0x18000
	v_lshl_add_u32 v0, v13, 12, v0
	v_and_b32_e32 v1, 1, v12
	s_addc_u32 s4, s15, 0
	v_lshl_or_b32 v0, v1, 6, v0
	v_mov_b64_e32 v[198:199], s[28:29]
	s_add_i32 s5, 0, 0x10000
	s_add_i32 s28, 0, 0x14000
	v_mov_b32_e32 v195, v193
	v_lshl_add_u32 v196, v14, 1, v0
	v_mov_b32_e32 v197, v193
	v_add_u32_e32 v221, s5, v220
	v_add_u32_e32 v222, s28, v220
	v_add_u32_e32 v223, 0, v2
	v_mov_b32_e32 v224, 0x358637bd
	s_movk_i32 s38, 0x2c00
	s_movk_i32 s39, 0x5800
	s_barrier
	s_mov_b32 s101, 0
	s_branch .LBB0_816

; #define PG8_BAR __builtin_amdgcn_s_barrier()
; template <class Epi, class Sched, bool ALIGN_EPI = false, bool SP2 = false>
; __device__ __forceinline__ void gemm_phase(PG8_LAS unsigned char* lds, const Gemm g, const Sched& S, const Epi& E, const int wave_id_in) {
;     ...
;         if constexpr (!Epi::AFTER_DRAIN) { E(acc, cur, wr, wc, fr, fq); if constexpr (Epi::PREF) { if (has_next) E.prefetch(nxt, wid); } S.done(cur); }
;         if (!has_next) break;
;         if constexpr (Epi::CARRY) {
;             const float keep = (cur.br == 0) ? 1.0f : 0.0f;
; #pragma unroll
;             for (int a = 0; a < 2; ++a)
; #pragma unroll
;                 for (int b = 0; b < 2; ++b)
; #pragma unroll
;                     for (int m = 0; m < 4; ++m)
; #pragma unroll
;                         for (int n = 0; n < 2; ++n) acc[a][b][m][n] = acc[a][b][m][n] * keep;
;         } else {
; #pragma unroll
;         for (int a = 0; a < 2; ++a)
; #pragma unroll
;             for (int b = 0; b < 2; ++b)
; #pragma unroll
;                 for (int m = 0; m < 4; ++m)
; #pragma unroll
;                     for (int n = 0; n < 2; ++n) acc[a][b][m][n] = (f32x4){0.f, 0.f, 0.f, 0.f};
;         }
;         cur = nxt; cA = nA; cB = nB; ++ui;
;         if constexpr (ALIGN_EPI) { if (wr == 1) PG8_BAR; }
.LBB0_815:
	s_mov_b32 s101, 1
	s_and_b64 vcc, exec, s[6:7]
	s_mov_b32 s8, s64
	s_mov_b32 s26, s66
	s_mov_b64 s[12:13], s[70:71]
	s_mov_b64 s[10:11], s[68:69]
	s_cbranch_vccnz .LBB0_876

;     __host__ __device__ bool next(int i, Unit& u) const { const long L = (long)i * G + c; if (L >= maxL) return false; return unit_of(L, u); }
;     __device__ __forceinline__ const char* a_base(const Gemm& g, const Unit& u, size_t tstep) const { return (const char*)g.A + (size_t)u.pm * tstep; }
;     __device__ __forceinline__ const char* b_base(const Gemm& g, const Unit& u, size_t tstep) const { return (const char*)g.Bt + (size_t)u.pn * tstep; }
; #define PG8_STAGE(bufoff, gbase, voff) do { _Pragma("unroll") for (int _i = 0; _i < 2; ++_i) \
;         __builtin_amdgcn_global_load_lds((const unsigned*)((const char*)(gbase) + (voff)[_i]), (PG8_LAS unsigned*)(lds + (bufoff) + ldsw + _i * 8192), 16, 0, 0); } while (0)
; #define PG8_WAIT_V(n) asm volatile("s_waitcnt vmcnt(" #n ")" ::: "memory")
; #define PG8_WAIT_L(n) asm volatile("s_waitcnt lgkmcnt(" #n ")" ::: "memory")
; template <class Epi, class Sched, bool ALIGN_EPI = false, bool SP2 = false>
; __device__ __forceinline__ void gemm_phase(PG8_LAS unsigned char* lds, const Gemm g, const Sched& S, const Epi& E, const int wave_id_in) {
;     ...
;         const bool has_next = S.next(ui + 1, nxt);
;         const char* nA = has_next ? S.a_base(g, nxt, tstep) : cA; const char* nB = has_next ? S.b_base(g, nxt, tstep) : cB;
;         for (int t = 0; t < nt; t += 2) {
;             const bool last = (t == nt - 2);
;             const char* a1 = cA + (size_t)(t + 1) * kstep;
;             const char* a2 = last ? nA : cA + (size_t)(t + 2) * kstep; const char* b2 = last ? nB : cB + (size_t)(t + 2) * kstep;
;             const char* a3 = a2 + kstep; const char* b3 = b2 + kstep;
;             if (last && has_next) S.a_ready(nxt);
;             if constexpr (SP2) {
;             PG8_LDB(B0, 0, 0); PG8_LDB(B1, 0, 1); PG8_SCHED; PG8_LDA(At, 0, 0); PG8_STAGE(PG8_SA(1, 1), a1 + hstep, voffA);
;             PG8_WAIT_V(8); PG8_WAIT_L(0); PG8_BAR; __builtin_amdgcn_s_setprio(1); PG8_MMA(0, 0, At, B0); PG8_MMA(0, 1, At, B1); __builtin_amdgcn_s_setprio(0); PG8_BAR; PG8_SCHED;
;             PG8_LDA(At, 0, 1); PG8_STAGE(PG8_SB(0, 0), b2, voffB); PG8_STAGE(PG8_SB(0, 1), b2 + hstep, voffB); PG8_STAGE(PG8_SA(0, 0), a2, voffA);
;             PG8_WAIT_V(8); PG8_WAIT_L(0); PG8_BAR; __builtin_amdgcn_s_setprio(1); PG8_MMA(1, 0, At, B0); PG8_MMA(1, 1, At, B1); __builtin_amdgcn_s_setprio(0); PG8_BAR; PG8_SCHED;
.LBB0_818:
	s_ashr_i32 s67, s66, 31
	s_lshl_b64 s[68:69], s[66:67], 20
	s_add_u32 s68, s78, s68
	s_addc_u32 s69, s79, s69
	s_and_b64 s[70:71], s[6:7], exec
	s_cselect_b32 s9, s69, s11
	s_cselect_b32 s27, s68, s10
	s_ashr_i32 s65, s64, 31
	s_lshl_b64 s[70:71], s[64:65], 20
	s_add_u32 s70, s44, s70
	s_addc_u32 s71, s45, s71
	s_and_b64 s[72:73], s[6:7], exec
	s_cselect_b32 s65, s71, s13
	s_cselect_b32 s74, s70, s12
	s_add_u32 s10, s10, 0x80080
	s_addc_u32 s11, s11, 0
	s_add_u32 s75, s12, 0x100
	s_addc_u32 vcc_lo, s13, 0
	s_mov_b32 vcc_hi, -2
	s_waitcnt lgkmcnt(0)
	ds_read_b128 v[44:47], v221
	ds_read_b128 v[48:51], v221 offset:1024
	ds_read_b128 v[56:59], v221 offset:2048
	s_waitcnt lgkmcnt(0)
	ds_read_b128 v[60:63], v221 offset:3072
	ds_read_b128 v[68:71], v222
	ds_read_b128 v[72:75], v222 offset:1024
	ds_read_b128 v[76:79], v222 offset:2048
	ds_read_b128 v[84:87], v222 offset:3072
	s_add_u32 s12, s10, 0xfff80080
	s_addc_u32 s13, s11, -1
	s_cmp_eq_u32 vcc_hi, 28
	s_cselect_b32 s73, s9, s13
	s_cselect_b32 s72, s27, s12
	s_cselect_b32 s13, s65, vcc_lo
	s_cselect_b32 s12, s74, s75
	v_lshl_add_u64 v[208:209], s[10:11], 0, v[194:195]
	s_add_i32 m0, s81, 0xc000
	ds_read_b128 v[92:95], v223
	ds_read_b128 v[96:99], v223 offset:1024
	ds_read_b128 v[120:123], v223 offset:2048
	ds_read_b128 v[124:127], v223 offset:3072
	ds_read_b128 v[168:171], v223 offset:4096
	ds_read_b128 v[180:183], v223 offset:5120
	ds_read_b128 v[200:203], v223 offset:6144
	ds_read_b128 v[204:207], v223 offset:7168
	global_load_lds_dwordx4 v[208:209], off
	v_lshl_add_u64 v[208:209], s[10:11], 0, v[196:197]
	s_add_i32 m0, s81, 0xe000
	s_nop 0
	global_load_lds_dwordx4 v[208:209], off
	s_cmp_lg_u32 s101, 0
	s_cbranch_scc1 .Lpw_ffnup_0_r
	s_waitcnt vmcnt(8)
	s_branch .Lpw_ffnup_0_j
.Lpw_ffnup_0_r:
	s_waitcnt vmcnt(22)
.Lpw_ffnup_0_j:
	s_waitcnt lgkmcnt(0)
	s_barrier
	s_setprio 1
	s_waitcnt lgkmcnt(0)
	v_mfma_f32_16x16x32_bf16 v[40:43], v[44:47], v[92:95], 0
	v_mfma_f32_16x16x32_bf16 v[36:39], v[56:59], v[92:95], 0
	v_mfma_f32_16x16x32_bf16 v[104:107], v[68:71], v[92:95], 0
	v_mfma_f32_16x16x32_bf16 v[92:95], v[76:79], v[92:95], 0
	v_mfma_f32_16x16x32_bf16 v[108:111], v[76:79], v[120:123], 0
	v_mfma_f32_16x16x32_bf16 v[40:43], v[48:51], v[96:99], v[40:43]
	v_mfma_f32_16x16x32_bf16 v[36:39], v[60:63], v[96:99], v[36:39]
	v_mfma_f32_16x16x32_bf16 v[172:175], v[44:47], v[120:123], 0
	v_mfma_f32_16x16x32_bf16 v[164:167], v[56:59], v[120:123], 0
	v_mfma_f32_16x16x32_bf16 v[104:107], v[72:75], v[96:99], v[104:107]
	v_mfma_f32_16x16x32_bf16 v[92:95], v[84:87], v[96:99], v[92:95]
	v_mfma_f32_16x16x32_bf16 v[96:99], v[68:71], v[120:123], 0
	v_mfma_f32_16x16x32_bf16 v[120:123], v[84:87], v[124:127], v[108:111]
	v_mfma_f32_16x16x32_bf16 v[108:111], v[68:71], v[168:171], 0
	v_mfma_f32_16x16x32_bf16 v[172:175], v[48:51], v[124:127], v[172:175]
	v_mfma_f32_16x16x32_bf16 v[164:167], v[60:63], v[124:127], v[164:167]
	v_mfma_f32_16x16x32_bf16 v[96:99], v[72:75], v[124:127], v[96:99]
	v_mfma_f32_16x16x32_bf16 v[124:127], v[72:75], v[180:183], v[108:111]
	v_mfma_f32_16x16x32_bf16 v[108:111], v[76:79], v[168:171], 0
	v_mfma_f32_16x16x32_bf16 v[136:139], v[84:87], v[180:183], v[108:111]
	v_mfma_f32_16x16x32_bf16 v[108:111], v[68:71], v[200:203], 0
	v_mfma_f32_16x16x32_bf16 v[156:159], v[44:47], v[168:171], 0
	v_mfma_f32_16x16x32_bf16 v[152:155], v[56:59], v[168:171], 0
	v_mfma_f32_16x16x32_bf16 v[160:163], v[44:47], v[200:203], 0
	v_mfma_f32_16x16x32_bf16 v[132:135], v[56:59], v[200:203], 0
	v_mfma_f32_16x16x32_bf16 v[116:119], v[72:75], v[204:207], v[108:111]
	v_mfma_f32_16x16x32_bf16 v[108:111], v[76:79], v[200:203], 0
	v_mfma_f32_16x16x32_bf16 v[156:159], v[48:51], v[180:183], v[156:159]
	v_mfma_f32_16x16x32_bf16 v[152:155], v[60:63], v[180:183], v[152:155]
	v_mfma_f32_16x16x32_bf16 v[160:163], v[48:51], v[204:207], v[160:163]
	v_mfma_f32_16x16x32_bf16 v[132:135], v[60:63], v[204:207], v[132:135]
	v_mfma_f32_16x16x32_bf16 v[112:115], v[84:87], v[204:207], v[108:111]
	s_setprio 0
	s_barrier
	s_add_i32 s40, s5, s80
	v_lshl_add_u64 v[216:217], s[12:13], 0, v[186:187]
	s_mov_b32 m0, s40
	ds_read_b128 v[108:111], v223 offset:16384
	ds_read_b128 v[140:143], v223 offset:17408
	ds_read_b128 v[144:147], v223 offset:18432
	ds_read_b128 v[148:151], v223 offset:19456
	ds_read_b128 v[168:171], v223 offset:20480
	ds_read_b128 v[180:183], v223 offset:21504
	ds_read_b128 v[200:203], v223 offset:22528
	ds_read_b128 v[204:207], v223 offset:23552
	global_load_lds_dwordx4 v[216:217], off
	s_add_i32 m0, s40, 0x2000
	s_add_u32 s40, s12, 0x80000
	v_lshl_add_u64 v[218:219], s[12:13], 0, v[190:191]
	s_addc_u32 s41, s13, 0
	s_add_i32 s77, s28, s80
	global_load_lds_dwordx4 v[218:219], off
	v_lshl_add_u64 v[208:209], s[40:41], 0, v[186:187]
	s_mov_b32 m0, s77
	v_lshl_add_u64 v[226:227], s[72:73], 0, v[184:185]
	global_load_lds_dwordx4 v[208:209], off
	v_lshl_add_u64 v[208:209], s[40:41], 0, v[190:191]
	s_add_i32 m0, s77, 0x2000
	v_lshl_add_u64 v[228:229], s[72:73], 0, v[188:189]
	global_load_lds_dwordx4 v[208:209], off
	s_mov_b32 m0, s81
	s_nop 0
	global_load_lds_dwordx4 v[226:227], off
	s_mov_b32 m0, s82
	s_nop 0
	global_load_lds_dwordx4 v[228:229], off
	s_cmp_lg_u32 s101, 0
	s_cbranch_scc1 .Lpw_ffnup_1_r
	s_waitcnt vmcnt(8)
	s_branch .Lpw_ffnup_1_j

; #define PG8_STAGE(bufoff, gbase, voff) do { _Pragma("unroll") for (int _i = 0; _i < 2; ++_i) \
;         __builtin_amdgcn_global_load_lds((const unsigned*)((const char*)(gbase) + (voff)[_i]), (PG8_LAS unsigned*)(lds + (bufoff) + ldsw + _i * 8192), 16, 0, 0); } while (0)
; #define PG8_LDA(dst, b, h) do { _Pragma("unroll") for (int m = 0; m < 4; ++m) _Pragma("unroll") for (int k = 0; k < 2; ++k) dst[m][k] = *(const PG8_LAS bf16x8*)(lds + PG8_SA(b, h) + aoff + m * 2048 + k * 1024); } while (0)
; #define PG8_LDB(dst, b, h) do { _Pragma("unroll") for (int n = 0; n < 2; ++n) _Pragma("unroll") for (int k = 0; k < 2; ++k) dst[n][k] = *(const PG8_LAS bf16x8*)(lds + PG8_SB(b, h) + boff + n * 2048 + k * 1024); } while (0)
; #define PG8_MMA(ai, bj, At, Bt) do { _Pragma("unroll") for (int m = 0; m < 4; ++m) _Pragma("unroll") for (int n = 0; n < 2; ++n) _Pragma("unroll") for (int k = 0; k < 2; ++k) \
;         acc[ai][bj][m][n] = __builtin_amdgcn_mfma_f32_16x16x32_bf16(Bt[n][k], At[m][k], acc[ai][bj][m][n], 0, 0, 0); } while (0)
; #define PG8_WAIT_V(n) asm volatile("s_waitcnt vmcnt(" #n ")" ::: "memory")
; #define PG8_WAIT_L(n) asm volatile("s_waitcnt lgkmcnt(" #n ")" ::: "memory")
; #define PG8_BAR __builtin_amdgcn_s_barrier()
; #define PG8_SCHED __builtin_amdgcn_sched_barrier(0)
; template <class Epi, class Sched, bool ALIGN_EPI = false, bool SP2 = false>
; __device__ __forceinline__ void gemm_phase(PG8_LAS unsigned char* lds, const Gemm g, const Sched& S, const Epi& E, const int wave_id_in) {
;     ...
;             PG8_WAIT_V(8); PG8_WAIT_L(0); PG8_BAR; __builtin_amdgcn_s_setprio(1); PG8_MMA(1, 0, At, B0); PG8_MMA(1, 1, At, B1); __builtin_amdgcn_s_setprio(0); PG8_BAR; PG8_SCHED;
;             PG8_LDB(B0, 1, 0); PG8_LDB(B1, 1, 1); PG8_SCHED; PG8_LDA(At, 1, 0); PG8_STAGE(PG8_SA(0, 1), a2 + hstep, voffA);
;             PG8_WAIT_V(8); PG8_WAIT_L(0); PG8_BAR; __builtin_amdgcn_s_setprio(1); PG8_MMA(0, 0, At, B0); PG8_MMA(0, 1, At, B1); __builtin_amdgcn_s_setprio(0); PG8_BAR; PG8_SCHED;
.Lpw_ffnup_1_j:
	s_waitcnt lgkmcnt(0)
	s_barrier
	s_setprio 1
	s_waitcnt lgkmcnt(0)
	v_mfma_f32_16x16x32_bf16 v[128:131], v[44:47], v[108:111], 0
	v_mfma_f32_16x16x32_bf16 v[64:67], v[56:59], v[108:111], 0
	v_mfma_f32_16x16x32_bf16 v[100:103], v[44:47], v[144:147], 0
	v_mfma_f32_16x16x32_bf16 v[88:91], v[56:59], v[144:147], 0
	v_mfma_f32_16x16x32_bf16 v[28:31], v[44:47], v[168:171], 0
	v_mfma_f32_16x16x32_bf16 v[24:27], v[56:59], v[168:171], 0
	v_mfma_f32_16x16x32_bf16 v[44:47], v[44:47], v[200:203], 0
	v_mfma_f32_16x16x32_bf16 v[32:35], v[76:79], v[108:111], 0
	v_mfma_f32_16x16x32_bf16 v[20:23], v[68:71], v[144:147], 0
	v_mfma_f32_16x16x32_bf16 v[16:19], v[76:79], v[144:147], 0
	v_mfma_f32_16x16x32_bf16 v[12:15], v[68:71], v[168:171], 0
	v_mfma_f32_16x16x32_bf16 v[8:11], v[76:79], v[168:171], 0
	v_mfma_f32_16x16x32_bf16 v[4:7], v[68:71], v[200:203], 0
	v_mfma_f32_16x16x32_bf16 v[0:3], v[76:79], v[200:203], 0
	v_mfma_f32_16x16x32_bf16 v[128:131], v[48:51], v[140:143], v[128:131]
	v_mfma_f32_16x16x32_bf16 v[64:67], v[60:63], v[140:143], v[64:67]
	v_mfma_f32_16x16x32_bf16 v[100:103], v[48:51], v[148:151], v[100:103]
	v_mfma_f32_16x16x32_bf16 v[88:91], v[60:63], v[148:151], v[88:91]
	v_mfma_f32_16x16x32_bf16 v[28:31], v[48:51], v[180:183], v[28:31]
	v_mfma_f32_16x16x32_bf16 v[24:27], v[60:63], v[180:183], v[24:27]
	v_mfma_f32_16x16x32_bf16 v[44:47], v[48:51], v[204:207], v[44:47]
	v_mfma_f32_16x16x32_bf16 v[48:51], v[56:59], v[200:203], 0
	v_mfma_f32_16x16x32_bf16 v[52:55], v[68:71], v[108:111], 0
	v_mfma_f32_16x16x32_bf16 v[32:35], v[84:87], v[140:143], v[32:35]
	v_mfma_f32_16x16x32_bf16 v[20:23], v[72:75], v[148:151], v[20:23]
	v_mfma_f32_16x16x32_bf16 v[16:19], v[84:87], v[148:151], v[16:19]
	v_mfma_f32_16x16x32_bf16 v[12:15], v[72:75], v[180:183], v[12:15]
	v_mfma_f32_16x16x32_bf16 v[8:11], v[84:87], v[180:183], v[8:11]
	v_mfma_f32_16x16x32_bf16 v[4:7], v[72:75], v[204:207], v[4:7]
	v_mfma_f32_16x16x32_bf16 v[0:3], v[84:87], v[204:207], v[0:3]
	v_mfma_f32_16x16x32_bf16 v[48:51], v[60:63], v[204:207], v[48:51]
	v_mfma_f32_16x16x32_bf16 v[56:59], v[72:75], v[140:143], v[52:55]
	s_setprio 0
	s_barrier
	s_add_i32 s77, 0, 0x18000
	s_add_i32 s76, 0, 0x1c000
	v_add_u32_e32 v72, s77, v220
	v_add_u32_e32 v80, s76, v220
	ds_read_b128 v[52:55], v72
	ds_read_b128 v[60:63], v72 offset:1024
	ds_read_b128 v[68:71], v72 offset:2048
	ds_read_b128 v[72:75], v72 offset:3072
	ds_read_b128 v[76:79], v80
	ds_read_b128 v[84:87], v80 offset:1024
	ds_read_b128 v[168:171], v80 offset:2048
	ds_read_b128 v[180:183], v80 offset:3072
	s_add_u32 s40, s72, 0x80000
	s_addc_u32 s41, s73, 0
	s_mov_b32 m0, s83
	v_lshl_add_u64 v[148:149], s[40:41], 0, v[184:185]
	ds_read_b128 v[80:83], v223 offset:32768
	ds_read_b128 v[108:111], v223 offset:33792
	ds_read_b128 v[140:143], v223 offset:34816
	ds_read_b128 v[144:147], v223 offset:35840
	ds_read_b128 v[176:179], v223 offset:36864
	ds_read_b128 v[200:203], v223 offset:37888
	ds_read_b128 v[204:207], v223 offset:38912
	ds_read_b128 v[208:211], v223 offset:39936
	global_load_lds_dwordx4 v[148:149], off
	v_lshl_add_u64 v[148:149], s[40:41], 0, v[188:189]
	s_mov_b32 m0, s84
	s_nop 0
	global_load_lds_dwordx4 v[148:149], off
	s_waitcnt vmcnt(8)
	s_waitcnt lgkmcnt(0)
	s_barrier
	s_setprio 1
	s_waitcnt lgkmcnt(0)
	v_mfma_f32_16x16x32_bf16 v[148:151], v[52:55], v[140:143], v[172:175]
	v_mfma_f32_16x16x32_bf16 v[172:175], v[60:63], v[144:147], v[148:151]
	v_mfma_f32_16x16x32_bf16 v[148:151], v[68:71], v[140:143], v[164:167]
	v_mfma_f32_16x16x32_bf16 v[164:167], v[72:75], v[144:147], v[148:151]
	v_mfma_f32_16x16x32_bf16 v[148:151], v[52:55], v[176:179], v[156:159]
	v_mfma_f32_16x16x32_bf16 v[40:43], v[52:55], v[80:83], v[40:43]
	v_mfma_f32_16x16x32_bf16 v[36:39], v[68:71], v[80:83], v[36:39]
	v_mfma_f32_16x16x32_bf16 v[156:159], v[60:63], v[200:203], v[148:151]
	v_mfma_f32_16x16x32_bf16 v[148:151], v[68:71], v[176:179], v[152:155]
	v_mfma_f32_16x16x32_bf16 v[104:107], v[76:79], v[80:83], v[104:107]
	v_mfma_f32_16x16x32_bf16 v[80:83], v[168:171], v[80:83], v[92:95]
	v_mfma_f32_16x16x32_bf16 v[40:43], v[60:63], v[108:111], v[40:43]
	v_mfma_f32_16x16x32_bf16 v[36:39], v[72:75], v[108:111], v[36:39]
	v_mfma_f32_16x16x32_bf16 v[152:155], v[72:75], v[200:203], v[148:151]
	v_mfma_f32_16x16x32_bf16 v[148:151], v[52:55], v[204:207], v[160:163]
	v_mfma_f32_16x16x32_bf16 v[104:107], v[84:87], v[108:111], v[104:107]
	v_mfma_f32_16x16x32_bf16 v[108:111], v[180:183], v[108:111], v[80:83]
	v_mfma_f32_16x16x32_bf16 v[80:83], v[76:79], v[140:143], v[96:99]
	v_mfma_f32_16x16x32_bf16 v[160:163], v[60:63], v[208:211], v[148:151]
	v_mfma_f32_16x16x32_bf16 v[148:151], v[84:87], v[144:147], v[80:83]
	v_mfma_f32_16x16x32_bf16 v[80:83], v[168:171], v[140:143], v[120:123]
	v_mfma_f32_16x16x32_bf16 v[144:147], v[180:183], v[144:147], v[80:83]
	v_mfma_f32_16x16x32_bf16 v[80:83], v[76:79], v[176:179], v[124:127]
	v_mfma_f32_16x16x32_bf16 v[140:143], v[84:87], v[200:203], v[80:83]
	v_mfma_f32_16x16x32_bf16 v[80:83], v[168:171], v[176:179], v[136:139]
	v_mfma_f32_16x16x32_bf16 v[136:139], v[180:183], v[200:203], v[80:83]
	v_mfma_f32_16x16x32_bf16 v[80:83], v[76:79], v[204:207], v[116:119]
	v_mfma_f32_16x16x32_bf16 v[132:135], v[68:71], v[204:207], v[132:135]
	v_mfma_f32_16x16x32_bf16 v[116:119], v[84:87], v[208:211], v[80:83]
	v_mfma_f32_16x16x32_bf16 v[80:83], v[168:171], v[204:207], v[112:115]
	v_mfma_f32_16x16x32_bf16 v[132:135], v[72:75], v[208:211], v[132:135]
	v_mfma_f32_16x16x32_bf16 v[112:115], v[180:183], v[208:211], v[80:83]
	s_setprio 0
	s_barrier
; #define PG8_STAGE(bufoff, gbase, voff) do { _Pragma("unroll") for (int _i = 0; _i < 2; ++_i) \
;         __builtin_amdgcn_global_load_lds((const unsigned*)((const char*)(gbase) + (voff)[_i]), (PG8_LAS unsigned*)(lds + (bufoff) + ldsw + _i * 8192), 16, 0, 0); } while (0)
; #define PG8_LDA(dst, b, h) do { _Pragma("unroll") for (int m = 0; m < 4; ++m) _Pragma("unroll") for (int k = 0; k < 2; ++k) dst[m][k] = *(const PG8_LAS bf16x8*)(lds + PG8_SA(b, h) + aoff + m * 2048 + k * 1024); } while (0)
; #define PG8_MMA(ai, bj, At, Bt) do { _Pragma("unroll") for (int m = 0; m < 4; ++m) _Pragma("unroll") for (int n = 0; n < 2; ++n) _Pragma("unroll") for (int k = 0; k < 2; ++k) \
;         acc[ai][bj][m][n] = __builtin_amdgcn_mfma_f32_16x16x32_bf16(Bt[n][k], At[m][k], acc[ai][bj][m][n], 0, 0, 0); } while (0)
; #define PG8_WAIT_V(n) asm volatile("s_waitcnt vmcnt(" #n ")" ::: "memory")
; #define PG8_WAIT_L(n) asm volatile("s_waitcnt lgkmcnt(" #n ")" ::: "memory")
; #define PG8_BAR __builtin_amdgcn_s_barrier()
; #define PG8_SCHED __builtin_amdgcn_sched_barrier(0)
; template <class Epi, class Sched, bool ALIGN_EPI = false, bool SP2 = false>
; __device__ __forceinline__ void gemm_phase(PG8_LAS unsigned char* lds, const Gemm g, const Sched& S, const Epi& E, const int wave_id_in) {
;     ...
;             PG8_LDA(At, 1, 1); PG8_STAGE(PG8_SB(1, 0), b3, voffB); PG8_STAGE(PG8_SB(1, 1), b3 + hstep, voffB); PG8_STAGE(PG8_SA(1, 0), a3, voffA);
;             PG8_WAIT_V(8); PG8_WAIT_L(0); PG8_BAR; __builtin_amdgcn_s_setprio(1); PG8_MMA(1, 0, At, B0); PG8_MMA(1, 1, At, B1); __builtin_amdgcn_s_setprio(0); PG8_BAR; PG8_SCHED;
	s_add_i32 s40, s77, s80
	s_nop 2
	v_lshl_add_u64 v[80:81], v[216:217], 0, s[34:35]
	s_mov_b32 m0, s40
	ds_read_b128 v[92:95], v223 offset:49152
	ds_read_b128 v[96:99], v223 offset:50176
	ds_read_b128 v[120:123], v223 offset:51200
	ds_read_b128 v[124:127], v223 offset:52224
	ds_read_b128 v[200:203], v223 offset:53248
	ds_read_b128 v[204:207], v223 offset:54272
	ds_read_b128 v[208:211], v223 offset:55296
	ds_read_b128 v[212:215], v223 offset:56320
	global_load_lds_dwordx4 v[80:81], off
	s_add_i32 m0, s40, 0x2000
	s_add_u32 s12, s12, 0x80080
	v_lshl_add_u64 v[80:81], v[218:219], 0, s[34:35]
	s_addc_u32 s13, s13, 0
	s_add_i32 s40, s76, s80
	global_load_lds_dwordx4 v[80:81], off
	v_lshl_add_u64 v[80:81], s[12:13], 0, v[186:187]
	s_mov_b32 m0, s40
	s_nop 0
	global_load_lds_dwordx4 v[80:81], off
	v_lshl_add_u64 v[80:81], s[12:13], 0, v[190:191]
	s_add_i32 m0, s40, 0x2000
	s_nop 0
	global_load_lds_dwordx4 v[80:81], off
	v_lshl_add_u64 v[80:81], v[226:227], 0, s[34:35]
	s_mov_b32 m0, s87
	s_nop 0
	global_load_lds_dwordx4 v[80:81], off
	v_lshl_add_u64 v[80:81], v[228:229], 0, s[34:35]
	s_mov_b32 m0, s88
	s_nop 0
	global_load_lds_dwordx4 v[80:81], off
	s_waitcnt vmcnt(8)
	s_waitcnt lgkmcnt(0)
	s_barrier
	s_setprio 1
	s_waitcnt lgkmcnt(0)
	v_mfma_f32_16x16x32_bf16 v[80:83], v[52:55], v[92:95], v[128:131]
	v_mfma_f32_16x16x32_bf16 v[44:47], v[52:55], v[208:211], v[44:47]
	v_mfma_f32_16x16x32_bf16 v[128:131], v[60:63], v[96:99], v[80:83]
	v_mfma_f32_16x16x32_bf16 v[80:83], v[52:55], v[120:123], v[100:103]
	v_mfma_f32_16x16x32_bf16 v[176:179], v[60:63], v[212:215], v[44:47]
	v_mfma_f32_16x16x32_bf16 v[44:47], v[68:71], v[208:211], v[48:51]
	v_mfma_f32_16x16x32_bf16 v[64:67], v[68:71], v[92:95], v[64:67]
	v_mfma_f32_16x16x32_bf16 v[100:103], v[60:63], v[124:127], v[80:83]
	v_mfma_f32_16x16x32_bf16 v[80:83], v[68:71], v[120:123], v[88:91]
	v_mfma_f32_16x16x32_bf16 v[28:31], v[52:55], v[200:203], v[28:31]
	v_mfma_f32_16x16x32_bf16 v[24:27], v[68:71], v[200:203], v[24:27]
	v_mfma_f32_16x16x32_bf16 v[52:55], v[72:75], v[212:215], v[44:47]
	v_mfma_f32_16x16x32_bf16 v[44:47], v[76:79], v[92:95], v[56:59]
	v_mfma_f32_16x16x32_bf16 v[32:35], v[168:171], v[92:95], v[32:35]
	v_mfma_f32_16x16x32_bf16 v[20:23], v[76:79], v[120:123], v[20:23]
	v_mfma_f32_16x16x32_bf16 v[16:19], v[168:171], v[120:123], v[16:19]
	v_mfma_f32_16x16x32_bf16 v[12:15], v[76:79], v[200:203], v[12:15]
	v_mfma_f32_16x16x32_bf16 v[8:11], v[168:171], v[200:203], v[8:11]
	v_mfma_f32_16x16x32_bf16 v[4:7], v[76:79], v[208:211], v[4:7]
	v_mfma_f32_16x16x32_bf16 v[0:3], v[168:171], v[208:211], v[0:3]
	v_mfma_f32_16x16x32_bf16 v[64:67], v[72:75], v[96:99], v[64:67]
	v_mfma_f32_16x16x32_bf16 v[88:91], v[72:75], v[124:127], v[80:83]
	v_mfma_f32_16x16x32_bf16 v[28:31], v[60:63], v[204:207], v[28:31]
	v_mfma_f32_16x16x32_bf16 v[24:27], v[72:75], v[204:207], v[24:27]
	v_mfma_f32_16x16x32_bf16 v[80:83], v[84:87], v[96:99], v[44:47]
	v_mfma_f32_16x16x32_bf16 v[32:35], v[180:183], v[96:99], v[32:35]
	v_mfma_f32_16x16x32_bf16 v[20:23], v[84:87], v[124:127], v[20:23]
	v_mfma_f32_16x16x32_bf16 v[16:19], v[180:183], v[124:127], v[16:19]
	v_mfma_f32_16x16x32_bf16 v[12:15], v[84:87], v[204:207], v[12:15]
	v_mfma_f32_16x16x32_bf16 v[8:11], v[180:183], v[204:207], v[8:11]
	v_mfma_f32_16x16x32_bf16 v[4:7], v[84:87], v[212:215], v[4:7]
	v_mfma_f32_16x16x32_bf16 v[0:3], v[180:183], v[212:215], v[0:3]
	s_setprio 0
	s_barrier
	s_add_i32 vcc_hi, vcc_hi, 2
	s_add_u32 s10, s10, 0x100
	s_addc_u32 s11, s11, 0
	s_add_u32 s75, s75, 0x100
	s_addc_u32 vcc_lo, vcc_lo, 0
	s_cmp_gt_u32 vcc_hi, 29
	s_cbranch_scc0 .LBB0_819
	s_branch .Lpeel_exit_ffnup
